# final epilogue: output stores without the nt hint (store acks from L2 no longer serialise the chunk loop)
# speedup vs baseline: 1.0072x; 1.0072x over previous
.LBB0_1466:
	v_lshl_or_b32 v128, s42, 8, v168
	v_lshl_add_u32 v164, s41, 8, v166
	s_ashr_i32 s16, s41, 5
	v_ashrrev_i32_e32 v129, 31, v128
	v_ashrrev_i32_e32 v165, 31, v164
	s_mul_hi_i32 s17, s16, 0x6000
	s_mulk_i32 s16, 0x6000
	v_or_b32_e32 v188, 16, v164
	v_lshl_add_u64 v[162:163], v[128:129], 1, s[10:11]
	v_lshlrev_b64 v[130:131], 11, v[164:165]
	s_add_u32 s16, s31, s16
	v_ashrrev_i32_e32 v189, 31, v188
	v_lshl_add_u64 v[130:131], v[162:163], 0, v[130:131]
	v_lshlrev_b64 v[160:161], 2, v[128:129]
	s_addc_u32 s17, s34, s17
	v_lshlrev_b64 v[180:181], 11, v[188:189]
	global_load_dwordx4 v[172:175], v[130:131], off nt
	global_load_dwordx4 v[176:179], v[130:131], off offset:256 nt
	v_lshl_add_u64 v[140:141], s[16:17], 0, v[160:161]
	v_lshl_add_u64 v[184:185], v[162:163], 0, v[180:181]
	global_load_dwordx4 v[136:139], v[140:141], off
	global_load_dwordx4 v[132:135], v[140:141], off offset:16
	global_load_dwordx4 v[128:131], v[140:141], off offset:528
	s_nop 0
	global_load_dwordx4 v[140:143], v[140:141], off offset:512
	s_nop 0
	global_load_dwordx4 v[180:183], v[184:185], off nt
	s_nop 0
	global_load_dwordx4 v[184:187], v[184:185], off offset:256 nt
	v_lshlrev_b64 v[190:191], 12, v[164:165]
	v_lshl_add_u64 v[190:191], s[82:83], 0, v[190:191]
	v_lshlrev_b64 v[188:189], 12, v[188:189]
	v_lshl_add_u64 v[190:191], v[190:191], 0, v[160:161]
	v_lshl_add_u64 v[188:189], s[82:83], 0, v[188:189]
	v_lshl_add_u64 v[188:189], v[188:189], 0, v[160:161]
	s_and_b64 vcc, exec, s[0:1]
	s_mov_b64 s[0:1], -1
	s_waitcnt vmcnt(0)
	v_lshlrev_b32_e32 v192, 16, v172
	v_and_b32_e32 v193, 0xffff0000, v172
	v_lshlrev_b32_e32 v172, 16, v173
	v_and_b32_e32 v173, 0xffff0000, v173
	v_lshlrev_b32_e32 v194, 16, v174
	v_and_b32_e32 v195, 0xffff0000, v174
	v_lshlrev_b32_e32 v174, 16, v175
	v_and_b32_e32 v175, 0xffff0000, v175
	v_lshlrev_b32_e32 v196, 16, v176
	v_and_b32_e32 v197, 0xffff0000, v176
	v_lshlrev_b32_e32 v176, 16, v177
	v_and_b32_e32 v177, 0xffff0000, v177
	v_lshlrev_b32_e32 v198, 16, v178
	v_and_b32_e32 v199, 0xffff0000, v178
	v_lshlrev_b32_e32 v178, 16, v179
	v_and_b32_e32 v179, 0xffff0000, v179
	v_pk_fma_f32 v[126:127], v[126:127], v[138:139], v[172:173]
	v_pk_fma_f32 v[124:125], v[124:125], v[136:137], v[192:193]
	v_pk_fma_f32 v[122:123], v[122:123], v[134:135], v[174:175]
	v_pk_fma_f32 v[114:115], v[114:115], v[142:143], v[176:177]
	v_pk_fma_f32 v[112:113], v[112:113], v[140:141], v[196:197]
	v_pk_fma_f32 v[106:107], v[106:107], v[130:131], v[178:179]
	v_lshlrev_b32_e32 v172, 16, v180
	v_and_b32_e32 v173, 0xffff0000, v180
	v_lshlrev_b32_e32 v174, 16, v181
	v_and_b32_e32 v175, 0xffff0000, v181
	v_lshlrev_b32_e32 v176, 16, v182
	v_and_b32_e32 v177, 0xffff0000, v182
	v_lshlrev_b32_e32 v178, 16, v183
	v_and_b32_e32 v179, 0xffff0000, v183
	v_lshlrev_b32_e32 v180, 16, v184
	v_and_b32_e32 v181, 0xffff0000, v184
	v_lshlrev_b32_e32 v182, 16, v185
	v_and_b32_e32 v183, 0xffff0000, v185
	v_lshlrev_b32_e32 v184, 16, v186
	v_and_b32_e32 v185, 0xffff0000, v186
	v_lshlrev_b32_e32 v186, 16, v187
	v_and_b32_e32 v187, 0xffff0000, v187
	v_pk_fma_f32 v[120:121], v[120:121], v[132:133], v[194:195]
	v_pk_fma_f32 v[104:105], v[104:105], v[128:129], v[198:199]
	v_pk_fma_f32 v[118:119], v[118:119], v[138:139], v[174:175]
	v_pk_fma_f32 v[116:117], v[116:117], v[136:137], v[172:173]
	v_pk_fma_f32 v[110:111], v[110:111], v[134:135], v[178:179]
	v_pk_fma_f32 v[108:109], v[108:109], v[132:133], v[176:177]
	v_pk_fma_f32 v[102:103], v[102:103], v[142:143], v[182:183]
	v_pk_fma_f32 v[100:101], v[100:101], v[140:141], v[180:181]
	v_pk_fma_f32 v[98:99], v[98:99], v[130:131], v[186:187]
	v_pk_fma_f32 v[96:97], v[96:97], v[128:129], v[184:185]
	global_store_dwordx4 v[190:191], v[124:127], off
	global_store_dwordx4 v[190:191], v[120:123], off offset:16
	global_store_dwordx4 v[190:191], v[112:115], off offset:512
	global_store_dwordx4 v[190:191], v[104:107], off offset:528
	global_store_dwordx4 v[188:189], v[116:119], off
	global_store_dwordx4 v[188:189], v[108:111], off offset:16
	global_store_dwordx4 v[188:189], v[100:103], off offset:512
	global_store_dwordx4 v[188:189], v[96:99], off offset:528
	v_or_b32_e32 v112, 32, v164
	v_or_b32_e32 v114, 48, v164
	v_ashrrev_i32_e32 v113, 31, v112
	v_ashrrev_i32_e32 v115, 31, v114
	v_lshlrev_b64 v[96:97], 11, v[112:113]
	v_lshlrev_b64 v[104:105], 11, v[114:115]
	v_lshl_add_u64 v[100:101], v[162:163], 0, v[96:97]
	v_lshl_add_u64 v[108:109], v[162:163], 0, v[104:105]
	global_load_dwordx4 v[96:99], v[100:101], off nt
	s_nop 0
	global_load_dwordx4 v[100:103], v[100:101], off offset:256 nt
	s_nop 0
	global_load_dwordx4 v[104:107], v[108:109], off nt
	s_nop 0
	global_load_dwordx4 v[108:111], v[108:109], off offset:256 nt
	v_lshlrev_b64 v[112:113], 12, v[112:113]
	v_lshlrev_b64 v[114:115], 12, v[114:115]
	v_lshl_add_u64 v[112:113], s[82:83], 0, v[112:113]
	v_lshl_add_u64 v[114:115], s[82:83], 0, v[114:115]
	v_lshl_add_u64 v[112:113], v[112:113], 0, v[160:161]
	v_add_u32_e32 v116, 0x80, v164
	v_lshl_add_u64 v[114:115], v[114:115], 0, v[160:161]
	v_ashrrev_i32_e32 v117, 31, v116
	v_lshlrev_b64 v[118:119], 11, v[116:117]
	v_lshl_add_u64 v[118:119], v[162:163], 0, v[118:119]
	s_waitcnt vmcnt(3)
	v_lshlrev_b32_e32 v120, 16, v96
	v_and_b32_e32 v121, 0xffff0000, v96
	v_lshlrev_b32_e32 v96, 16, v97
	v_and_b32_e32 v97, 0xffff0000, v97
	s_waitcnt vmcnt(1)
	v_lshlrev_b32_e32 v174, 16, v106
	v_and_b32_e32 v175, 0xffff0000, v106
	v_lshlrev_b32_e32 v122, 16, v98
	v_and_b32_e32 v123, 0xffff0000, v98
	v_lshlrev_b32_e32 v98, 16, v99
	v_and_b32_e32 v99, 0xffff0000, v99
	v_lshlrev_b32_e32 v124, 16, v100
	v_and_b32_e32 v125, 0xffff0000, v100
	v_lshlrev_b32_e32 v100, 16, v101
	v_and_b32_e32 v101, 0xffff0000, v101
	v_lshlrev_b32_e32 v126, 16, v102
	v_and_b32_e32 v127, 0xffff0000, v102
	v_lshlrev_b32_e32 v102, 16, v103
	v_and_b32_e32 v103, 0xffff0000, v103
	v_lshlrev_b32_e32 v172, 16, v104
	v_and_b32_e32 v173, 0xffff0000, v104
	v_lshlrev_b32_e32 v104, 16, v105
	v_and_b32_e32 v105, 0xffff0000, v105
	v_lshlrev_b32_e32 v106, 16, v107
	v_and_b32_e32 v107, 0xffff0000, v107
	s_waitcnt vmcnt(0)
	v_lshlrev_b32_e32 v176, 16, v108
	v_and_b32_e32 v177, 0xffff0000, v108
	v_lshlrev_b32_e32 v108, 16, v109
	v_and_b32_e32 v109, 0xffff0000, v109
	v_lshlrev_b32_e32 v178, 16, v110
	v_and_b32_e32 v179, 0xffff0000, v110
	v_lshlrev_b32_e32 v110, 16, v111
	v_and_b32_e32 v111, 0xffff0000, v111
	v_pk_fma_f32 v[94:95], v[94:95], v[138:139], v[96:97]
	v_pk_fma_f32 v[92:93], v[92:93], v[136:137], v[120:121]
	v_pk_fma_f32 v[80:81], v[80:81], v[132:133], v[174:175]
	v_pk_fma_f32 v[90:91], v[90:91], v[134:135], v[98:99]
	v_pk_fma_f32 v[88:89], v[88:89], v[132:133], v[122:123]
	v_pk_fma_f32 v[78:79], v[78:79], v[142:143], v[100:101]
	v_pk_fma_f32 v[76:77], v[76:77], v[140:141], v[124:125]
	v_pk_fma_f32 v[74:75], v[74:75], v[130:131], v[102:103]
	v_pk_fma_f32 v[72:73], v[72:73], v[128:129], v[126:127]
	v_pk_fma_f32 v[86:87], v[86:87], v[138:139], v[104:105]
	v_pk_fma_f32 v[84:85], v[84:85], v[136:137], v[172:173]
	v_pk_fma_f32 v[82:83], v[82:83], v[134:135], v[106:107]
	v_pk_fma_f32 v[70:71], v[70:71], v[142:143], v[108:109]
	v_pk_fma_f32 v[68:69], v[68:69], v[140:141], v[176:177]
	v_pk_fma_f32 v[66:67], v[66:67], v[130:131], v[110:111]
	v_pk_fma_f32 v[64:65], v[64:65], v[128:129], v[178:179]
	global_store_dwordx4 v[112:113], v[92:95], off
	global_store_dwordx4 v[112:113], v[88:91], off offset:16
	global_store_dwordx4 v[112:113], v[76:79], off offset:512
	global_store_dwordx4 v[112:113], v[72:75], off offset:528
	global_store_dwordx4 v[114:115], v[84:87], off
	global_store_dwordx4 v[114:115], v[80:83], off offset:16
	global_store_dwordx4 v[114:115], v[68:71], off offset:512
	global_store_dwordx4 v[114:115], v[64:67], off offset:528
	v_add_u32_e32 v80, 0x90, v164
	v_ashrrev_i32_e32 v81, 31, v80
	v_lshlrev_b64 v[72:73], 11, v[80:81]
	v_lshl_add_u64 v[76:77], v[162:163], 0, v[72:73]
	global_load_dwordx4 v[64:67], v[118:119], off nt
	global_load_dwordx4 v[68:71], v[118:119], off offset:256 nt
	global_load_dwordx4 v[72:75], v[76:77], off nt
	s_nop 0
	global_load_dwordx4 v[76:79], v[76:77], off offset:256 nt
	v_lshlrev_b64 v[84:85], 12, v[116:117]
	v_lshlrev_b64 v[80:81], 12, v[80:81]
	v_lshl_add_u64 v[84:85], s[82:83], 0, v[84:85]
	v_lshl_add_u64 v[80:81], s[82:83], 0, v[80:81]
	v_lshl_add_u64 v[84:85], v[84:85], 0, v[160:161]
	v_add_u32_e32 v82, 0xa0, v164
	v_lshl_add_u64 v[80:81], v[80:81], 0, v[160:161]
	v_ashrrev_i32_e32 v83, 31, v82
	v_lshlrev_b64 v[86:87], 11, v[82:83]
	v_lshl_add_u64 v[86:87], v[162:163], 0, v[86:87]
	s_waitcnt vmcnt(3)
	v_lshlrev_b32_e32 v88, 16, v64
	v_and_b32_e32 v89, 0xffff0000, v64
	v_lshlrev_b32_e32 v64, 16, v65
	v_and_b32_e32 v65, 0xffff0000, v65
	s_waitcnt vmcnt(1)
	v_lshlrev_b32_e32 v98, 16, v74
	v_and_b32_e32 v99, 0xffff0000, v74
	v_lshlrev_b32_e32 v90, 16, v66
	v_and_b32_e32 v91, 0xffff0000, v66
	v_lshlrev_b32_e32 v66, 16, v67
	v_and_b32_e32 v67, 0xffff0000, v67
	v_lshlrev_b32_e32 v92, 16, v68
	v_and_b32_e32 v93, 0xffff0000, v68
	v_lshlrev_b32_e32 v68, 16, v69
	v_and_b32_e32 v69, 0xffff0000, v69
	v_lshlrev_b32_e32 v94, 16, v70
	v_and_b32_e32 v95, 0xffff0000, v70
	v_lshlrev_b32_e32 v70, 16, v71
	v_and_b32_e32 v71, 0xffff0000, v71
	v_lshlrev_b32_e32 v96, 16, v72
	v_and_b32_e32 v97, 0xffff0000, v72
	v_lshlrev_b32_e32 v72, 16, v73
	v_and_b32_e32 v73, 0xffff0000, v73
	v_lshlrev_b32_e32 v74, 16, v75
	v_and_b32_e32 v75, 0xffff0000, v75
	s_waitcnt vmcnt(0)
	v_lshlrev_b32_e32 v100, 16, v76
	v_and_b32_e32 v101, 0xffff0000, v76
	v_lshlrev_b32_e32 v76, 16, v77
	v_and_b32_e32 v77, 0xffff0000, v77
	v_lshlrev_b32_e32 v102, 16, v78
	v_and_b32_e32 v103, 0xffff0000, v78
	v_lshlrev_b32_e32 v78, 16, v79
	v_and_b32_e32 v79, 0xffff0000, v79
	v_pk_fma_f32 v[62:63], v[62:63], v[138:139], v[64:65]
	v_pk_fma_f32 v[60:61], v[60:61], v[136:137], v[88:89]
	v_pk_fma_f32 v[48:49], v[48:49], v[132:133], v[98:99]
	v_pk_fma_f32 v[58:59], v[58:59], v[134:135], v[66:67]
	v_pk_fma_f32 v[56:57], v[56:57], v[132:133], v[90:91]
	v_pk_fma_f32 v[46:47], v[46:47], v[142:143], v[68:69]
	v_pk_fma_f32 v[44:45], v[44:45], v[140:141], v[92:93]
	v_pk_fma_f32 v[42:43], v[42:43], v[130:131], v[70:71]
	v_pk_fma_f32 v[40:41], v[40:41], v[128:129], v[94:95]
	v_pk_fma_f32 v[54:55], v[54:55], v[138:139], v[72:73]
	v_pk_fma_f32 v[52:53], v[52:53], v[136:137], v[96:97]
	v_pk_fma_f32 v[50:51], v[50:51], v[134:135], v[74:75]
	v_pk_fma_f32 v[38:39], v[38:39], v[142:143], v[76:77]
	v_pk_fma_f32 v[36:37], v[36:37], v[140:141], v[100:101]
	v_pk_fma_f32 v[34:35], v[34:35], v[130:131], v[78:79]
	v_pk_fma_f32 v[32:33], v[32:33], v[128:129], v[102:103]
	global_store_dwordx4 v[84:85], v[60:63], off
	global_store_dwordx4 v[84:85], v[56:59], off offset:16
	global_store_dwordx4 v[84:85], v[44:47], off offset:512
	global_store_dwordx4 v[84:85], v[40:43], off offset:528
	global_store_dwordx4 v[80:81], v[52:55], off
	global_store_dwordx4 v[80:81], v[48:51], off offset:16
	global_store_dwordx4 v[80:81], v[36:39], off offset:512
	global_store_dwordx4 v[80:81], v[32:35], off offset:528
	v_add_u32_e32 v48, 0xb0, v164
	v_ashrrev_i32_e32 v49, 31, v48
	v_lshlrev_b64 v[40:41], 11, v[48:49]
	v_lshl_add_u64 v[50:51], v[162:163], 0, v[40:41]
	global_load_dwordx4 v[32:35], v[86:87], off nt
	global_load_dwordx4 v[36:39], v[86:87], off offset:256 nt
	global_load_dwordx4 v[40:43], v[50:51], off nt
	global_load_dwordx4 v[44:47], v[50:51], off offset:256 nt
	v_lshlrev_b64 v[50:51], 12, v[82:83]
	v_lshlrev_b64 v[48:49], 12, v[48:49]
	v_lshl_add_u64 v[50:51], s[82:83], 0, v[50:51]
	v_lshl_add_u64 v[48:49], s[82:83], 0, v[48:49]
	v_lshl_add_u64 v[50:51], v[50:51], 0, v[160:161]
	v_lshl_add_u64 v[48:49], v[48:49], 0, v[160:161]
	s_waitcnt vmcnt(3)
	v_lshlrev_b32_e32 v52, 16, v32
	v_and_b32_e32 v53, 0xffff0000, v32
	v_lshlrev_b32_e32 v32, 16, v33
	v_and_b32_e32 v33, 0xffff0000, v33
	v_lshlrev_b32_e32 v54, 16, v34
	v_and_b32_e32 v55, 0xffff0000, v34
	v_lshlrev_b32_e32 v34, 16, v35
	v_and_b32_e32 v35, 0xffff0000, v35
	s_waitcnt vmcnt(2)
	v_lshlrev_b32_e32 v56, 16, v36
	v_and_b32_e32 v57, 0xffff0000, v36
	v_lshlrev_b32_e32 v36, 16, v37
	v_and_b32_e32 v37, 0xffff0000, v37
	v_lshlrev_b32_e32 v58, 16, v38
	v_and_b32_e32 v59, 0xffff0000, v38
	v_lshlrev_b32_e32 v38, 16, v39
	v_and_b32_e32 v39, 0xffff0000, v39
	s_waitcnt vmcnt(1)
	v_lshlrev_b32_e32 v60, 16, v40
	v_and_b32_e32 v61, 0xffff0000, v40
	v_lshlrev_b32_e32 v40, 16, v41
	v_and_b32_e32 v41, 0xffff0000, v41
	v_lshlrev_b32_e32 v62, 16, v42
	v_and_b32_e32 v63, 0xffff0000, v42
	v_lshlrev_b32_e32 v42, 16, v43
	v_and_b32_e32 v43, 0xffff0000, v43
	s_waitcnt vmcnt(0)
	v_lshlrev_b32_e32 v64, 16, v44
	v_and_b32_e32 v65, 0xffff0000, v44
	v_lshlrev_b32_e32 v44, 16, v45
	v_and_b32_e32 v45, 0xffff0000, v45
	v_lshlrev_b32_e32 v66, 16, v46
	v_and_b32_e32 v67, 0xffff0000, v46
	v_lshlrev_b32_e32 v46, 16, v47
	v_and_b32_e32 v47, 0xffff0000, v47
	v_pk_fma_f32 v[30:31], v[30:31], v[138:139], v[32:33]
	v_pk_fma_f32 v[28:29], v[28:29], v[136:137], v[52:53]
	v_pk_fma_f32 v[26:27], v[26:27], v[134:135], v[34:35]
	v_pk_fma_f32 v[24:25], v[24:25], v[132:133], v[54:55]
	v_pk_fma_f32 v[14:15], v[14:15], v[142:143], v[36:37]
	v_pk_fma_f32 v[12:13], v[12:13], v[140:141], v[56:57]
	v_pk_fma_f32 v[10:11], v[10:11], v[130:131], v[38:39]
	v_pk_fma_f32 v[8:9], v[8:9], v[128:129], v[58:59]
	v_pk_fma_f32 v[22:23], v[22:23], v[138:139], v[40:41]
	v_pk_fma_f32 v[20:21], v[20:21], v[136:137], v[60:61]
	v_pk_fma_f32 v[18:19], v[18:19], v[134:135], v[42:43]
	v_pk_fma_f32 v[16:17], v[16:17], v[132:133], v[62:63]
	v_pk_fma_f32 v[6:7], v[6:7], v[142:143], v[44:45]
	v_pk_fma_f32 v[4:5], v[4:5], v[140:141], v[64:65]
	v_pk_fma_f32 v[2:3], v[2:3], v[130:131], v[46:47]
	v_pk_fma_f32 v[0:1], v[0:1], v[128:129], v[66:67]
	global_store_dwordx4 v[50:51], v[28:31], off
	global_store_dwordx4 v[50:51], v[24:27], off offset:16
	global_store_dwordx4 v[50:51], v[12:15], off offset:512
	global_store_dwordx4 v[50:51], v[8:11], off offset:528
	global_store_dwordx4 v[48:49], v[20:23], off
	global_store_dwordx4 v[48:49], v[16:19], off offset:16
	global_store_dwordx4 v[48:49], v[4:7], off offset:512
	global_store_dwordx4 v[48:49], v[0:3], off offset:528
	s_cbranch_vccnz .LBB0_1451
	s_andn2_b64 vcc, exec, s[6:7]
	s_cbranch_vccnz .LBB0_1450
	s_barrier
	s_branch .LBB0_1450
